# stagger 3 sleeps (~10.5 us) instead of 4
# speedup vs baseline: 1.0038x; 1.0022x over previous
.LBB0_539:
	s_or_b64 exec, exec, s[0:1]
	v_mov_b32_e32 v0, v154
	v_readlane_b32 s6, v253, 0
	s_waitcnt lgkmcnt(0)
	s_barrier
	v_readlane_b32 s8, v253, 0
	s_bitcmp1_b32 s8, 0
	s_cbranch_scc0 .Lstag_skip
	s_sleep 127
	s_sleep 127
	s_sleep 127
.Lstag_skip:
	s_cmpk_gt_i32 s6, 0xff
	s_cbranch_scc1 .LBB0_546
	v_readlane_b32 s0, v254, 24
	v_readlane_b32 s1, v254, 60
	s_add_u32 s7, s0, s1
	v_readlane_b32 s0, v254, 25
	s_addc_u32 s8, s0, 0
	s_lshl_b32 s9, s6, 3
	s_branch .LBB0_542
